# attention epilogue: lane pairs 16 apart exchange 8-byte pieces (v_permlane16_swap) so the O rows go out as 8 dwordx4 stores of 64 contiguous bytes per row instead of 16 dwordx2 stores
# speedup vs baseline: 1.0247x; 1.0006x over previous
.LBB0_248:
	ds_bpermute_b32 v0, v159, v222
	s_lshl_b32 s0, s14, 14
	s_add_u32 s0, s0, s15
	s_addc_u32 s8, 0, s16
	s_ashr_i32 s9, s18, 31
	s_waitcnt lgkmcnt(0)
	v_add_f32_e32 v2, v222, v0
	ds_bpermute_b32 v3, v160, v2
	s_add_u32 s0, s0, s18
	s_addc_u32 s8, s8, s9
	v_or_b32_e32 v0, s0, v165
	v_mov_b32_e32 v1, s8
	s_waitcnt lgkmcnt(0)
	v_add_f32_e32 v2, v2, v3
	v_rcp_f32_e32 v4, v2
	v_lshlrev_b64 v[0:1], 12, v[0:1]
	v_lshl_add_u64 v[0:1], s[6:7], 0, v[0:1]
	s_lshl_b32 s0, s13, 1
	v_lshl_add_u64 v[0:1], v[0:1], 0, s[0:1]
	v_and_b32_e32 v64, 8, v158
	v_mad_u32_u24 v64, v64, 3, v158
	v_lshl_add_u64 v[6:7], v[0:1], 0, v[64:65]
	v_pk_mul_f32 v[0:1], v[96:97], v[4:5] op_sel_hi:[1,0]
	v_pk_mul_f32 v[2:3], v[98:99], v[4:5] op_sel_hi:[1,0]
	v_pk_mul_f32 v[12:13], v[88:89], v[4:5] op_sel_hi:[1,0]
	v_pk_mul_f32 v[14:15], v[90:91], v[4:5] op_sel_hi:[1,0]
	v_cvt_pk_bf16_f32 v0, v0, v1
	v_cvt_pk_bf16_f32 v1, v2, v3
	v_cvt_pk_bf16_f32 v2, v12, v13
	v_cvt_pk_bf16_f32 v3, v14, v15
	s_nop 1
	v_permlane16_swap_b32_e32 v0, v2
	v_permlane16_swap_b32_e32 v1, v3
	global_store_dwordx4 v[6:7], v[0:3], off offset:0 nt
	s_add_i32 s12, s12, s42
	s_add_i32 s10, s10, s11
	v_pk_mul_f32 v[8:9], v[80:81], v[4:5] op_sel_hi:[1,0]
	v_pk_mul_f32 v[10:11], v[82:83], v[4:5] op_sel_hi:[1,0]
	v_pk_mul_f32 v[12:13], v[72:73], v[4:5] op_sel_hi:[1,0]
	v_pk_mul_f32 v[14:15], v[74:75], v[4:5] op_sel_hi:[1,0]
	v_cvt_pk_bf16_f32 v8, v8, v9
	v_cvt_pk_bf16_f32 v9, v10, v11
	v_cvt_pk_bf16_f32 v10, v12, v13
	v_cvt_pk_bf16_f32 v11, v14, v15
	s_nop 1
	v_permlane16_swap_b32_e32 v8, v10
	v_permlane16_swap_b32_e32 v9, v11
	global_store_dwordx4 v[6:7], v[8:11], off offset:64 nt
	v_pk_mul_f32 v[0:1], v[56:57], v[4:5] op_sel_hi:[1,0]
	v_pk_mul_f32 v[2:3], v[58:59], v[4:5] op_sel_hi:[1,0]
	v_pk_mul_f32 v[12:13], v[48:49], v[4:5] op_sel_hi:[1,0]
	v_pk_mul_f32 v[14:15], v[50:51], v[4:5] op_sel_hi:[1,0]
	v_cvt_pk_bf16_f32 v0, v0, v1
	v_cvt_pk_bf16_f32 v1, v2, v3
	v_cvt_pk_bf16_f32 v2, v12, v13
	v_cvt_pk_bf16_f32 v3, v14, v15
	s_nop 1
	v_permlane16_swap_b32_e32 v0, v2
	v_permlane16_swap_b32_e32 v1, v3
	global_store_dwordx4 v[6:7], v[0:3], off offset:128 nt
	v_pk_mul_f32 v[8:9], v[40:41], v[4:5] op_sel_hi:[1,0]
	v_pk_mul_f32 v[10:11], v[42:43], v[4:5] op_sel_hi:[1,0]
	v_pk_mul_f32 v[12:13], v[32:33], v[4:5] op_sel_hi:[1,0]
	v_pk_mul_f32 v[14:15], v[34:35], v[4:5] op_sel_hi:[1,0]
	v_cvt_pk_bf16_f32 v8, v8, v9
	v_cvt_pk_bf16_f32 v9, v10, v11
	v_cvt_pk_bf16_f32 v10, v12, v13
	v_cvt_pk_bf16_f32 v11, v14, v15
	s_nop 1
	v_permlane16_swap_b32_e32 v8, v10
	v_permlane16_swap_b32_e32 v9, v11
	global_store_dwordx4 v[6:7], v[8:11], off offset:192 nt
	v_pk_mul_f32 v[0:1], v[92:93], v[4:5] op_sel_hi:[1,0]
	v_pk_mul_f32 v[2:3], v[94:95], v[4:5] op_sel_hi:[1,0]
	v_pk_mul_f32 v[12:13], v[84:85], v[4:5] op_sel_hi:[1,0]
	v_pk_mul_f32 v[14:15], v[86:87], v[4:5] op_sel_hi:[1,0]
	v_cvt_pk_bf16_f32 v0, v0, v1
	v_cvt_pk_bf16_f32 v1, v2, v3
	v_cvt_pk_bf16_f32 v2, v12, v13
	v_cvt_pk_bf16_f32 v3, v14, v15
	s_nop 1
	v_permlane16_swap_b32_e32 v0, v2
	v_permlane16_swap_b32_e32 v1, v3
	global_store_dwordx4 v[6:7], v[0:3], off offset:256 nt
	v_pk_mul_f32 v[8:9], v[76:77], v[4:5] op_sel_hi:[1,0]
	v_pk_mul_f32 v[10:11], v[78:79], v[4:5] op_sel_hi:[1,0]
	v_pk_mul_f32 v[12:13], v[68:69], v[4:5] op_sel_hi:[1,0]
	v_pk_mul_f32 v[14:15], v[70:71], v[4:5] op_sel_hi:[1,0]
	v_cvt_pk_bf16_f32 v8, v8, v9
	v_cvt_pk_bf16_f32 v9, v10, v11
	v_cvt_pk_bf16_f32 v10, v12, v13
	v_cvt_pk_bf16_f32 v11, v14, v15
	s_nop 1
	v_permlane16_swap_b32_e32 v8, v10
	v_permlane16_swap_b32_e32 v9, v11
	global_store_dwordx4 v[6:7], v[8:11], off offset:320 nt
	v_pk_mul_f32 v[0:1], v[60:61], v[4:5] op_sel_hi:[1,0]
	v_pk_mul_f32 v[2:3], v[62:63], v[4:5] op_sel_hi:[1,0]
	v_pk_mul_f32 v[12:13], v[52:53], v[4:5] op_sel_hi:[1,0]
	v_pk_mul_f32 v[14:15], v[54:55], v[4:5] op_sel_hi:[1,0]
	v_cvt_pk_bf16_f32 v0, v0, v1
	v_cvt_pk_bf16_f32 v1, v2, v3
	v_cvt_pk_bf16_f32 v2, v12, v13
	v_cvt_pk_bf16_f32 v3, v14, v15
	s_nop 1
	v_permlane16_swap_b32_e32 v0, v2
	v_permlane16_swap_b32_e32 v1, v3
	global_store_dwordx4 v[6:7], v[0:3], off offset:384 nt
	v_pk_mul_f32 v[8:9], v[44:45], v[4:5] op_sel_hi:[1,0]
	v_pk_mul_f32 v[10:11], v[46:47], v[4:5] op_sel_hi:[1,0]
	v_pk_mul_f32 v[12:13], v[36:37], v[4:5] op_sel_hi:[1,0]
	v_pk_mul_f32 v[14:15], v[38:39], v[4:5] op_sel_hi:[1,0]
	v_cvt_pk_bf16_f32 v8, v8, v9
	v_cvt_pk_bf16_f32 v9, v10, v11
	v_cvt_pk_bf16_f32 v10, v12, v13
	v_cvt_pk_bf16_f32 v11, v14, v15
	s_nop 1
	v_permlane16_swap_b32_e32 v8, v10
	v_permlane16_swap_b32_e32 v9, v11
	global_store_dwordx4 v[6:7], v[8:11], off offset:448 nt
	s_cmpk_gt_i32 s12, 0x7ff
	s_nop 0
	s_cbranch_scc1 .LBB0_262
